# P6 and P9 K-loops touch the next row phase's HBM inputs (x rows for P7, X1 rows for P10) with one dummy load per iteration while HBM is idle; the two following vmcnt waits allow the extra operation
# speedup vs baseline: 1.0116x; 1.0091x over previous
.LBB0_871:
	s_ashr_i32 s45, s44, 31
	s_lshl_b64 s[46:47], s[44:45], 19
	s_add_u32 s46, s62, s46
	s_addc_u32 s47, s63, s47
	s_and_b64 s[48:49], s[4:5], exec
	s_cselect_b32 s45, s47, s57
	s_cselect_b32 s53, s46, s56
	s_ashr_i32 s43, s42, 31
	s_lshl_b64 s[48:49], s[42:43], 19
	s_add_u32 s48, s3, s48
	s_addc_u32 s49, s16, s49
	s_and_b64 s[60:61], s[4:5], exec
	s_cselect_b32 s43, s49, s59
	s_cselect_b32 s69, s48, s58
	s_add_u32 s56, s56, 0x40080
	s_addc_u32 s57, s57, 0
	s_add_u32 s70, s58, 0x100
	v_mov_b32_e32 v32, 0
	s_addc_u32 s71, s59, 0
	s_mov_b32 s72, -2
	v_mov_b32_e32 v33, v32
	v_mov_b32_e32 v34, v32
	v_mov_b32_e32 v35, v32
	v_mov_b32_e32 v36, v32
	v_mov_b32_e32 v37, v32
	v_mov_b32_e32 v38, v32
	v_mov_b32_e32 v39, v32
	v_mov_b32_e32 v48, v32
	v_mov_b32_e32 v49, v32
	v_mov_b32_e32 v50, v32
	v_mov_b32_e32 v51, v32
	v_mov_b32_e32 v52, v32
	v_mov_b32_e32 v53, v32
	v_mov_b32_e32 v54, v32
	v_mov_b32_e32 v55, v32
	v_mov_b32_e32 v64, v32
	v_mov_b32_e32 v65, v32
	v_mov_b32_e32 v66, v32
	v_mov_b32_e32 v67, v32
	v_mov_b32_e32 v68, v32
	v_mov_b32_e32 v69, v32
	v_mov_b32_e32 v70, v32
	v_mov_b32_e32 v71, v32
	v_mov_b32_e32 v80, v32
	v_mov_b32_e32 v81, v32
	v_mov_b32_e32 v82, v32
	v_mov_b32_e32 v83, v32
	v_mov_b32_e32 v84, v32
	v_mov_b32_e32 v85, v32
	v_mov_b32_e32 v86, v32
	v_mov_b32_e32 v87, v32
	v_mov_b32_e32 v40, v32
	v_mov_b32_e32 v41, v32
	v_mov_b32_e32 v42, v32
	v_mov_b32_e32 v43, v32
	v_mov_b32_e32 v44, v32
	v_mov_b32_e32 v45, v32
	v_mov_b32_e32 v46, v32
	v_mov_b32_e32 v47, v32
	v_mov_b32_e32 v56, v32
	v_mov_b32_e32 v57, v32
	v_mov_b32_e32 v58, v32
	v_mov_b32_e32 v59, v32
	v_mov_b32_e32 v60, v32
	v_mov_b32_e32 v61, v32
	v_mov_b32_e32 v62, v32
	v_mov_b32_e32 v63, v32
	v_mov_b32_e32 v72, v32
	v_mov_b32_e32 v73, v32
	v_mov_b32_e32 v74, v32
	v_mov_b32_e32 v75, v32
	v_mov_b32_e32 v76, v32
	v_mov_b32_e32 v77, v32
	v_mov_b32_e32 v78, v32
	v_mov_b32_e32 v79, v32
	v_mov_b32_e32 v88, v32
	v_mov_b32_e32 v89, v32
	v_mov_b32_e32 v90, v32
	v_mov_b32_e32 v91, v32
	v_mov_b32_e32 v92, v32
	v_mov_b32_e32 v93, v32
	v_mov_b32_e32 v94, v32
	v_mov_b32_e32 v95, v32
	v_mov_b32_e32 v96, v32
	v_mov_b32_e32 v97, v32
	v_mov_b32_e32 v98, v32
	v_mov_b32_e32 v99, v32
	v_mov_b32_e32 v100, v32
	v_mov_b32_e32 v101, v32
	v_mov_b32_e32 v102, v32
	v_mov_b32_e32 v103, v32
	v_mov_b32_e32 v112, v32
	v_mov_b32_e32 v113, v32
	v_mov_b32_e32 v114, v32
	v_mov_b32_e32 v115, v32
	v_mov_b32_e32 v116, v32
	v_mov_b32_e32 v117, v32
	v_mov_b32_e32 v118, v32
	v_mov_b32_e32 v119, v32
	v_mov_b32_e32 v128, v32
	v_mov_b32_e32 v129, v32
	v_mov_b32_e32 v130, v32
	v_mov_b32_e32 v131, v32
	v_mov_b32_e32 v132, v32
	v_mov_b32_e32 v133, v32
	v_mov_b32_e32 v134, v32
	v_mov_b32_e32 v135, v32
	v_mov_b32_e32 v144, v32
	v_mov_b32_e32 v145, v32
	v_mov_b32_e32 v146, v32
	v_mov_b32_e32 v147, v32
	v_mov_b32_e32 v148, v32
	v_mov_b32_e32 v149, v32
	v_mov_b32_e32 v150, v32
	v_mov_b32_e32 v151, v32
	v_mov_b32_e32 v104, v32
	v_mov_b32_e32 v105, v32
	v_mov_b32_e32 v106, v32
	v_mov_b32_e32 v107, v32
	v_mov_b32_e32 v108, v32
	v_mov_b32_e32 v109, v32
	v_mov_b32_e32 v110, v32
	v_mov_b32_e32 v111, v32
	v_mov_b32_e32 v120, v32
	v_mov_b32_e32 v121, v32
	v_mov_b32_e32 v122, v32
	v_mov_b32_e32 v123, v32
	v_mov_b32_e32 v124, v32
	v_mov_b32_e32 v125, v32
	v_mov_b32_e32 v126, v32
	v_mov_b32_e32 v127, v32
	v_mov_b32_e32 v136, v32
	v_mov_b32_e32 v137, v32
	v_mov_b32_e32 v138, v32
	v_mov_b32_e32 v139, v32
	v_mov_b32_e32 v140, v32
	v_mov_b32_e32 v141, v32
	v_mov_b32_e32 v142, v32
	v_mov_b32_e32 v143, v32
	v_mov_b32_e32 v152, v32
	v_mov_b32_e32 v153, v32
	v_mov_b32_e32 v154, v32
	v_mov_b32_e32 v155, v32
	v_mov_b32_e32 v156, v32
	v_mov_b32_e32 v157, v32
	v_mov_b32_e32 v158, v32
	v_mov_b32_e32 v159, v32
	v_readfirstlane_b32 s78, v184
	s_lshr_b32 s78, s78, 6
	s_lshl_b32 s79, s2, 3
	s_add_u32 s78, s78, s79
	s_lshl_b32 s78, s78, 13
	v_readlane_b32 s80, v254, 10
	v_readlane_b32 s81, v254, 11
	v_readlane_b32 s82, v254, 12
	v_readlane_b32 s83, v254, 13
	s_add_u32 s80, s80, s78
	s_addc_u32 s81, s81, 0
	s_add_u32 s82, s82, s78
	s_addc_u32 s83, s83, 0
	v_mbcnt_hi_u32_b32 v228, -1, v185
	v_lshlrev_b32_e32 v228, 6, v228
.LBB0_872:
	ds_read_b128 v[16:19], v191
	ds_read_b128 v[20:23], v191 offset:1024
	ds_read_b128 v[24:27], v191 offset:2048
	ds_read_b128 v[28:31], v191 offset:3072
	ds_read_b128 v[0:3], v192
	ds_read_b128 v[4:7], v192 offset:1024
	ds_read_b128 v[8:11], v192 offset:2048
	ds_read_b128 v[12:15], v192 offset:3072
	s_add_u32 s58, s56, 0xfffc0080
	s_addc_u32 s59, s57, -1
	s_cmp_eq_u32 s72, 12
	s_cselect_b32 s61, s45, s59
	s_cselect_b32 s60, s53, s58
	s_cselect_b32 s59, s43, s71
	s_cselect_b32 s58, s69, s70
	v_lshl_add_u64 v[218:219], s[56:57], 0, v[168:169]
	s_add_i32 m0, s18, 0xc000
	ds_read_b128 v[176:179], v193
	ds_read_b128 v[180:183], v193 offset:1024
	ds_read_b128 v[194:197], v193 offset:2048
	ds_read_b128 v[198:201], v193 offset:3072
	ds_read_b128 v[202:205], v193 offset:4096
	ds_read_b128 v[206:209], v193 offset:5120
	ds_read_b128 v[210:213], v193 offset:6144
	ds_read_b128 v[214:217], v193 offset:7168
	global_load_lds_dwordx4 v[218:219], off
	v_lshl_add_u64 v[218:219], s[56:57], 0, v[170:171]
	s_add_i32 m0, s18, 0xe000
	s_nop 0
	global_load_lds_dwordx4 v[218:219], off
	s_waitcnt vmcnt(8)
	s_add_u32 s79, s72, 2
	s_bitcmp1_b32 s79, 3
	s_cselect_b64 s[84:85], s[82:83], s[80:81]
	s_bfe_u32 s86, s79, 0x10002
	s_lshl_b32 s86, s86, 24
	s_bfe_u32 s87, s79, 0x10001
	s_lshl_b32 s87, s87, 12
	s_add_u32 s86, s86, s87
	v_add_u32_e32 v229, s86, v228
	global_load_dword v230, v229, s[84:85]
	s_nop 0
	s_waitcnt lgkmcnt(0)
	s_barrier
	s_setprio 1
	s_waitcnt lgkmcnt(0)
	v_mfma_scale_f32_16x16x128_f8f6f4 v[156:159], v[16:23], v[176:183], v[156:159], v186, v187 op_sel_hi:[0,0,0]
	v_mfma_scale_f32_16x16x128_f8f6f4 v[152:155], v[24:31], v[176:183], v[152:155], v186, v187 op_sel_hi:[0,0,0]
	v_mfma_scale_f32_16x16x128_f8f6f4 v[140:143], v[16:23], v[194:201], v[140:143], v186, v187 op_sel_hi:[0,0,0]
	v_mfma_scale_f32_16x16x128_f8f6f4 v[136:139], v[24:31], v[194:201], v[136:139], v186, v187 op_sel_hi:[0,0,0]
	v_mfma_scale_f32_16x16x128_f8f6f4 v[124:127], v[16:23], v[202:209], v[124:127], v186, v187 op_sel_hi:[0,0,0]
	v_mfma_scale_f32_16x16x128_f8f6f4 v[120:123], v[24:31], v[202:209], v[120:123], v186, v187 op_sel_hi:[0,0,0]
	v_mfma_scale_f32_16x16x128_f8f6f4 v[108:111], v[16:23], v[210:217], v[108:111], v186, v187 op_sel_hi:[0,0,0]
	v_mfma_scale_f32_16x16x128_f8f6f4 v[104:107], v[24:31], v[210:217], v[104:107], v186, v187 op_sel_hi:[0,0,0]
	s_setprio 0
	s_setprio 1
	v_mfma_scale_f32_16x16x128_f8f6f4 v[148:151], v[0:7], v[176:183], v[148:151], v186, v187 op_sel_hi:[0,0,0]
	v_mfma_scale_f32_16x16x128_f8f6f4 v[144:147], v[8:15], v[176:183], v[144:147], v186, v187 op_sel_hi:[0,0,0]
	v_mfma_scale_f32_16x16x128_f8f6f4 v[132:135], v[0:7], v[194:201], v[132:135], v186, v187 op_sel_hi:[0,0,0]
	v_mfma_scale_f32_16x16x128_f8f6f4 v[128:131], v[8:15], v[194:201], v[128:131], v186, v187 op_sel_hi:[0,0,0]
	v_mfma_scale_f32_16x16x128_f8f6f4 v[116:119], v[0:7], v[202:209], v[116:119], v186, v187 op_sel_hi:[0,0,0]
	v_mfma_scale_f32_16x16x128_f8f6f4 v[112:115], v[8:15], v[202:209], v[112:115], v186, v187 op_sel_hi:[0,0,0]
	v_mfma_scale_f32_16x16x128_f8f6f4 v[100:103], v[0:7], v[210:217], v[100:103], v186, v187 op_sel_hi:[0,0,0]
	v_mfma_scale_f32_16x16x128_f8f6f4 v[96:99], v[8:15], v[210:217], v[96:99], v186, v187 op_sel_hi:[0,0,0]
	s_setprio 0
	s_barrier
	s_add_i32 s73, s67, s17
	v_lshl_add_u64 v[176:177], s[58:59], 0, v[162:163]
	s_mov_b32 m0, s73
	ds_read_b128 v[194:197], v193 offset:16384
	ds_read_b128 v[198:201], v193 offset:17408
	ds_read_b128 v[202:205], v193 offset:18432
	ds_read_b128 v[206:209], v193 offset:19456
	ds_read_b128 v[210:213], v193 offset:20480
	ds_read_b128 v[214:217], v193 offset:21504
	ds_read_b128 v[218:221], v193 offset:22528
	ds_read_b128 v[222:225], v193 offset:23552
	global_load_lds_dwordx4 v[176:177], off
	s_add_i32 m0, s73, 0x2000
	s_add_u32 s74, s58, 0x40000
	v_lshl_add_u64 v[178:179], s[58:59], 0, v[166:167]
	s_addc_u32 s75, s59, 0
	s_add_i32 s73, s68, s17
	global_load_lds_dwordx4 v[178:179], off
	v_lshl_add_u64 v[180:181], s[74:75], 0, v[162:163]
	s_mov_b32 m0, s73
	v_lshl_add_u64 v[182:183], s[60:61], 0, v[164:165]
	global_load_lds_dwordx4 v[180:181], off
	v_lshl_add_u64 v[180:181], s[74:75], 0, v[166:167]
	s_add_i32 m0, s73, 0x2000
	s_nop 0
	global_load_lds_dwordx4 v[180:181], off
	v_lshl_add_u64 v[180:181], s[60:61], 0, v[160:161]
	s_mov_b32 m0, s18
	s_nop 0
	global_load_lds_dwordx4 v[180:181], off
	s_mov_b32 m0, s19
	s_nop 0
	global_load_lds_dwordx4 v[182:183], off
	s_waitcnt vmcnt(9)
	s_waitcnt lgkmcnt(0)
	s_barrier
	s_setprio 1
	s_waitcnt lgkmcnt(0)
	v_mfma_scale_f32_16x16x128_f8f6f4 v[92:95], v[16:23], v[194:201], v[92:95], v186, v187 op_sel_hi:[0,0,0]
	v_mfma_scale_f32_16x16x128_f8f6f4 v[88:91], v[24:31], v[194:201], v[88:91], v186, v187 op_sel_hi:[0,0,0]
	v_mfma_scale_f32_16x16x128_f8f6f4 v[76:79], v[16:23], v[202:209], v[76:79], v186, v187 op_sel_hi:[0,0,0]
	v_mfma_scale_f32_16x16x128_f8f6f4 v[72:75], v[24:31], v[202:209], v[72:75], v186, v187 op_sel_hi:[0,0,0]
	v_mfma_scale_f32_16x16x128_f8f6f4 v[60:63], v[16:23], v[210:217], v[60:63], v186, v187 op_sel_hi:[0,0,0]
	v_mfma_scale_f32_16x16x128_f8f6f4 v[56:59], v[24:31], v[210:217], v[56:59], v186, v187 op_sel_hi:[0,0,0]
	v_mfma_scale_f32_16x16x128_f8f6f4 v[44:47], v[16:23], v[218:225], v[44:47], v186, v187 op_sel_hi:[0,0,0]
	v_mfma_scale_f32_16x16x128_f8f6f4 v[40:43], v[24:31], v[218:225], v[40:43], v186, v187 op_sel_hi:[0,0,0]
	s_setprio 0
	s_setprio 1
	v_mfma_scale_f32_16x16x128_f8f6f4 v[84:87], v[0:7], v[194:201], v[84:87], v186, v187 op_sel_hi:[0,0,0]
	v_mfma_scale_f32_16x16x128_f8f6f4 v[80:83], v[8:15], v[194:201], v[80:83], v186, v187 op_sel_hi:[0,0,0]
	v_mfma_scale_f32_16x16x128_f8f6f4 v[68:71], v[0:7], v[202:209], v[68:71], v186, v187 op_sel_hi:[0,0,0]
	v_mfma_scale_f32_16x16x128_f8f6f4 v[64:67], v[8:15], v[202:209], v[64:67], v186, v187 op_sel_hi:[0,0,0]
	v_mfma_scale_f32_16x16x128_f8f6f4 v[52:55], v[0:7], v[210:217], v[52:55], v186, v187 op_sel_hi:[0,0,0]
	v_mfma_scale_f32_16x16x128_f8f6f4 v[48:51], v[8:15], v[210:217], v[48:51], v186, v187 op_sel_hi:[0,0,0]
	v_mfma_scale_f32_16x16x128_f8f6f4 v[36:39], v[0:7], v[218:225], v[36:39], v186, v187 op_sel_hi:[0,0,0]
	v_mfma_scale_f32_16x16x128_f8f6f4 v[32:35], v[8:15], v[218:225], v[32:35], v186, v187 op_sel_hi:[0,0,0]
	s_setprio 0
	s_barrier
	s_add_i32 s73, 0, 0x18000
	s_add_i32 s74, 0, 0x1c000
	v_add_u32_e32 v12, s73, v189
	v_add_u32_e32 v28, s74, v189
	ds_read_b128 v[0:3], v12
	ds_read_b128 v[4:7], v12 offset:1024
	ds_read_b128 v[8:11], v12 offset:2048
	ds_read_b128 v[12:15], v12 offset:3072
	ds_read_b128 v[16:19], v28
	ds_read_b128 v[20:23], v28 offset:1024
	ds_read_b128 v[24:27], v28 offset:2048
	ds_read_b128 v[28:31], v28 offset:3072
	s_add_u32 s60, s60, 0x40000
	s_addc_u32 s61, s61, 0
	s_mov_b32 m0, s26
	v_lshl_add_u64 v[226:227], s[60:61], 0, v[160:161]
	ds_read_b128 v[194:197], v193 offset:32768
	ds_read_b128 v[198:201], v193 offset:33792
	ds_read_b128 v[202:205], v193 offset:34816
	ds_read_b128 v[206:209], v193 offset:35840
	ds_read_b128 v[210:213], v193 offset:36864
	ds_read_b128 v[214:217], v193 offset:37888
	ds_read_b128 v[218:221], v193 offset:38912
	ds_read_b128 v[222:225], v193 offset:39936
	global_load_lds_dwordx4 v[226:227], off
	v_lshl_add_u64 v[226:227], s[60:61], 0, v[164:165]
	s_mov_b32 m0, s27
	s_nop 0
	global_load_lds_dwordx4 v[226:227], off
	s_waitcnt vmcnt(9)
	s_waitcnt lgkmcnt(0)
	s_barrier
	s_setprio 1
	s_waitcnt lgkmcnt(0)
	v_mfma_scale_f32_16x16x128_f8f6f4 v[156:159], v[0:7], v[194:201], v[156:159], v186, v187 op_sel_hi:[0,0,0]
	v_mfma_scale_f32_16x16x128_f8f6f4 v[152:155], v[8:15], v[194:201], v[152:155], v186, v187 op_sel_hi:[0,0,0]
	v_mfma_scale_f32_16x16x128_f8f6f4 v[140:143], v[0:7], v[202:209], v[140:143], v186, v187 op_sel_hi:[0,0,0]
	v_mfma_scale_f32_16x16x128_f8f6f4 v[136:139], v[8:15], v[202:209], v[136:139], v186, v187 op_sel_hi:[0,0,0]
	v_mfma_scale_f32_16x16x128_f8f6f4 v[124:127], v[0:7], v[210:217], v[124:127], v186, v187 op_sel_hi:[0,0,0]
	v_mfma_scale_f32_16x16x128_f8f6f4 v[120:123], v[8:15], v[210:217], v[120:123], v186, v187 op_sel_hi:[0,0,0]
	v_mfma_scale_f32_16x16x128_f8f6f4 v[108:111], v[0:7], v[218:225], v[108:111], v186, v187 op_sel_hi:[0,0,0]
	v_mfma_scale_f32_16x16x128_f8f6f4 v[104:107], v[8:15], v[218:225], v[104:107], v186, v187 op_sel_hi:[0,0,0]
	s_setprio 0
	s_setprio 1
	v_mfma_scale_f32_16x16x128_f8f6f4 v[148:151], v[16:23], v[194:201], v[148:151], v186, v187 op_sel_hi:[0,0,0]
	v_mfma_scale_f32_16x16x128_f8f6f4 v[144:147], v[24:31], v[194:201], v[144:147], v186, v187 op_sel_hi:[0,0,0]
	v_mfma_scale_f32_16x16x128_f8f6f4 v[132:135], v[16:23], v[202:209], v[132:135], v186, v187 op_sel_hi:[0,0,0]
	v_mfma_scale_f32_16x16x128_f8f6f4 v[128:131], v[24:31], v[202:209], v[128:131], v186, v187 op_sel_hi:[0,0,0]
	v_mfma_scale_f32_16x16x128_f8f6f4 v[116:119], v[16:23], v[210:217], v[116:119], v186, v187 op_sel_hi:[0,0,0]
	v_mfma_scale_f32_16x16x128_f8f6f4 v[112:115], v[24:31], v[210:217], v[112:115], v186, v187 op_sel_hi:[0,0,0]
	v_mfma_scale_f32_16x16x128_f8f6f4 v[100:103], v[16:23], v[218:225], v[100:103], v186, v187 op_sel_hi:[0,0,0]
	v_mfma_scale_f32_16x16x128_f8f6f4 v[96:99], v[24:31], v[218:225], v[96:99], v186, v187 op_sel_hi:[0,0,0]
	s_setprio 0
	s_barrier
	s_add_i32 s60, s73, s17
	v_lshl_add_u64 v[176:177], v[176:177], 0, s[10:11]
	s_mov_b32 m0, s60
	ds_read_b128 v[194:197], v193 offset:49152
	ds_read_b128 v[198:201], v193 offset:50176
	ds_read_b128 v[202:205], v193 offset:51200
	ds_read_b128 v[206:209], v193 offset:52224
	ds_read_b128 v[210:213], v193 offset:53248
	ds_read_b128 v[214:217], v193 offset:54272
	ds_read_b128 v[218:221], v193 offset:55296
	ds_read_b128 v[222:225], v193 offset:56320
	global_load_lds_dwordx4 v[176:177], off
	s_add_i32 m0, s60, 0x2000
	s_add_u32 s58, s58, 0x40080
	v_lshl_add_u64 v[176:177], v[178:179], 0, s[10:11]
	s_addc_u32 s59, s59, 0
	s_add_i32 s60, s74, s17
	global_load_lds_dwordx4 v[176:177], off
	v_lshl_add_u64 v[176:177], s[58:59], 0, v[162:163]
	s_mov_b32 m0, s60
	s_nop 0
	global_load_lds_dwordx4 v[176:177], off
	v_lshl_add_u64 v[176:177], s[58:59], 0, v[166:167]
	s_add_i32 m0, s60, 0x2000
	s_nop 0
	global_load_lds_dwordx4 v[176:177], off
	v_lshl_add_u64 v[176:177], v[180:181], 0, s[10:11]
	s_mov_b32 m0, s35
	s_nop 0
	global_load_lds_dwordx4 v[176:177], off
	v_lshl_add_u64 v[176:177], v[182:183], 0, s[10:11]
	s_mov_b32 m0, s55
	s_nop 0
	global_load_lds_dwordx4 v[176:177], off
	s_waitcnt vmcnt(8)
	s_waitcnt lgkmcnt(0)
	s_barrier
	s_setprio 1
	s_waitcnt lgkmcnt(0)
	v_mfma_scale_f32_16x16x128_f8f6f4 v[92:95], v[0:7], v[194:201], v[92:95], v186, v187 op_sel_hi:[0,0,0]
	v_mfma_scale_f32_16x16x128_f8f6f4 v[88:91], v[8:15], v[194:201], v[88:91], v186, v187 op_sel_hi:[0,0,0]
	v_mfma_scale_f32_16x16x128_f8f6f4 v[76:79], v[0:7], v[202:209], v[76:79], v186, v187 op_sel_hi:[0,0,0]
	v_mfma_scale_f32_16x16x128_f8f6f4 v[72:75], v[8:15], v[202:209], v[72:75], v186, v187 op_sel_hi:[0,0,0]
	v_mfma_scale_f32_16x16x128_f8f6f4 v[60:63], v[0:7], v[210:217], v[60:63], v186, v187 op_sel_hi:[0,0,0]
	v_mfma_scale_f32_16x16x128_f8f6f4 v[56:59], v[8:15], v[210:217], v[56:59], v186, v187 op_sel_hi:[0,0,0]
	v_mfma_scale_f32_16x16x128_f8f6f4 v[44:47], v[0:7], v[218:225], v[44:47], v186, v187 op_sel_hi:[0,0,0]
	v_mfma_scale_f32_16x16x128_f8f6f4 v[40:43], v[8:15], v[218:225], v[40:43], v186, v187 op_sel_hi:[0,0,0]
	s_setprio 0
	s_setprio 1
	v_mfma_scale_f32_16x16x128_f8f6f4 v[84:87], v[16:23], v[194:201], v[84:87], v186, v187 op_sel_hi:[0,0,0]
	v_mfma_scale_f32_16x16x128_f8f6f4 v[80:83], v[24:31], v[194:201], v[80:83], v186, v187 op_sel_hi:[0,0,0]
	v_mfma_scale_f32_16x16x128_f8f6f4 v[68:71], v[16:23], v[202:209], v[68:71], v186, v187 op_sel_hi:[0,0,0]
	v_mfma_scale_f32_16x16x128_f8f6f4 v[64:67], v[24:31], v[202:209], v[64:67], v186, v187 op_sel_hi:[0,0,0]
	v_mfma_scale_f32_16x16x128_f8f6f4 v[52:55], v[16:23], v[210:217], v[52:55], v186, v187 op_sel_hi:[0,0,0]
	v_mfma_scale_f32_16x16x128_f8f6f4 v[48:51], v[24:31], v[210:217], v[48:51], v186, v187 op_sel_hi:[0,0,0]
	v_mfma_scale_f32_16x16x128_f8f6f4 v[36:39], v[16:23], v[218:225], v[36:39], v186, v187 op_sel_hi:[0,0,0]
	v_mfma_scale_f32_16x16x128_f8f6f4 v[32:35], v[24:31], v[218:225], v[32:35], v186, v187 op_sel_hi:[0,0,0]
	s_setprio 0
	s_barrier
	s_add_i32 s72, s72, 2
	s_add_u32 s56, s56, 0x100
	s_addc_u32 s57, s57, 0
	s_add_u32 s70, s70, 0x100
	s_addc_u32 s71, s71, 0
	s_cmp_gt_u32 s72, 13
	s_cbranch_scc0 .LBB0_872
	s_and_b64 vcc, exec, s[12:13]
	s_cbranch_vccz .LBB0_875
	s_barrier

.LBB0_1194:
	s_ashr_i32 s39, s38, 31
	s_lshl_b64 s[40:41], s[38:39], 21
	s_add_u32 s40, s50, s40
	s_addc_u32 s41, s51, s41
	s_and_b64 s[42:43], s[0:1], exec
	s_cselect_b32 s39, s41, s49
	s_cselect_b32 s45, s40, s48
	s_ashr_i32 s37, s36, 31
	s_lshl_b64 s[42:43], s[36:37], 21
	s_add_u32 s42, s3, s42
	s_addc_u32 s43, s16, s43
	s_and_b64 s[54:55], s[0:1], exec
	s_cselect_b32 s37, s43, s53
	s_cselect_b32 s63, s42, s52
	s_add_u32 s48, s48, 0x100080
	s_addc_u32 s49, s49, 0
	s_add_u32 s64, s52, 0x100
	v_mov_b32_e32 v32, 0
	s_addc_u32 s65, s53, 0
	s_mov_b32 s66, -2
	v_mov_b32_e32 v33, v32
	v_mov_b32_e32 v34, v32
	v_mov_b32_e32 v35, v32
	v_mov_b32_e32 v36, v32
	v_mov_b32_e32 v37, v32
	v_mov_b32_e32 v38, v32
	v_mov_b32_e32 v39, v32
	v_mov_b32_e32 v48, v32
	v_mov_b32_e32 v49, v32
	v_mov_b32_e32 v50, v32
	v_mov_b32_e32 v51, v32
	v_mov_b32_e32 v52, v32
	v_mov_b32_e32 v53, v32
	v_mov_b32_e32 v54, v32
	v_mov_b32_e32 v55, v32
	v_mov_b32_e32 v64, v32
	v_mov_b32_e32 v65, v32
	v_mov_b32_e32 v66, v32
	v_mov_b32_e32 v67, v32
	v_mov_b32_e32 v68, v32
	v_mov_b32_e32 v69, v32
	v_mov_b32_e32 v70, v32
	v_mov_b32_e32 v71, v32
	v_mov_b32_e32 v80, v32
	v_mov_b32_e32 v81, v32
	v_mov_b32_e32 v82, v32
	v_mov_b32_e32 v83, v32
	v_mov_b32_e32 v84, v32
	v_mov_b32_e32 v85, v32
	v_mov_b32_e32 v86, v32
	v_mov_b32_e32 v87, v32
	v_mov_b32_e32 v40, v32
	v_mov_b32_e32 v41, v32
	v_mov_b32_e32 v42, v32
	v_mov_b32_e32 v43, v32
	v_mov_b32_e32 v44, v32
	v_mov_b32_e32 v45, v32
	v_mov_b32_e32 v46, v32
	v_mov_b32_e32 v47, v32
	v_mov_b32_e32 v56, v32
	v_mov_b32_e32 v57, v32
	v_mov_b32_e32 v58, v32
	v_mov_b32_e32 v59, v32
	v_mov_b32_e32 v60, v32
	v_mov_b32_e32 v61, v32
	v_mov_b32_e32 v62, v32
	v_mov_b32_e32 v63, v32
	v_mov_b32_e32 v72, v32
	v_mov_b32_e32 v73, v32
	v_mov_b32_e32 v74, v32
	v_mov_b32_e32 v75, v32
	v_mov_b32_e32 v76, v32
	v_mov_b32_e32 v77, v32
	v_mov_b32_e32 v78, v32
	v_mov_b32_e32 v79, v32
	v_mov_b32_e32 v88, v32
	v_mov_b32_e32 v89, v32
	v_mov_b32_e32 v90, v32
	v_mov_b32_e32 v91, v32
	v_mov_b32_e32 v92, v32
	v_mov_b32_e32 v93, v32
	v_mov_b32_e32 v94, v32
	v_mov_b32_e32 v95, v32
	v_mov_b32_e32 v96, v32
	v_mov_b32_e32 v97, v32
	v_mov_b32_e32 v98, v32
	v_mov_b32_e32 v99, v32
	v_mov_b32_e32 v100, v32
	v_mov_b32_e32 v101, v32
	v_mov_b32_e32 v102, v32
	v_mov_b32_e32 v103, v32
	v_mov_b32_e32 v112, v32
	v_mov_b32_e32 v113, v32
	v_mov_b32_e32 v114, v32
	v_mov_b32_e32 v115, v32
	v_mov_b32_e32 v116, v32
	v_mov_b32_e32 v117, v32
	v_mov_b32_e32 v118, v32
	v_mov_b32_e32 v119, v32
	v_mov_b32_e32 v128, v32
	v_mov_b32_e32 v129, v32
	v_mov_b32_e32 v130, v32
	v_mov_b32_e32 v131, v32
	v_mov_b32_e32 v132, v32
	v_mov_b32_e32 v133, v32
	v_mov_b32_e32 v134, v32
	v_mov_b32_e32 v135, v32
	v_mov_b32_e32 v144, v32
	v_mov_b32_e32 v145, v32
	v_mov_b32_e32 v146, v32
	v_mov_b32_e32 v147, v32
	v_mov_b32_e32 v148, v32
	v_mov_b32_e32 v149, v32
	v_mov_b32_e32 v150, v32
	v_mov_b32_e32 v151, v32
	v_mov_b32_e32 v104, v32
	v_mov_b32_e32 v105, v32
	v_mov_b32_e32 v106, v32
	v_mov_b32_e32 v107, v32
	v_mov_b32_e32 v108, v32
	v_mov_b32_e32 v109, v32
	v_mov_b32_e32 v110, v32
	v_mov_b32_e32 v111, v32
	v_mov_b32_e32 v120, v32
	v_mov_b32_e32 v121, v32
	v_mov_b32_e32 v122, v32
	v_mov_b32_e32 v123, v32
	v_mov_b32_e32 v124, v32
	v_mov_b32_e32 v125, v32
	v_mov_b32_e32 v126, v32
	v_mov_b32_e32 v127, v32
	v_mov_b32_e32 v136, v32
	v_mov_b32_e32 v137, v32
	v_mov_b32_e32 v138, v32
	v_mov_b32_e32 v139, v32
	v_mov_b32_e32 v140, v32
	v_mov_b32_e32 v141, v32
	v_mov_b32_e32 v142, v32
	v_mov_b32_e32 v143, v32
	v_mov_b32_e32 v152, v32
	v_mov_b32_e32 v153, v32
	v_mov_b32_e32 v154, v32
	v_mov_b32_e32 v155, v32
	v_mov_b32_e32 v156, v32
	v_mov_b32_e32 v157, v32
	v_mov_b32_e32 v158, v32
	v_mov_b32_e32 v159, v32
	v_readfirstlane_b32 s78, v184
	s_lshr_b32 s78, s78, 6
	s_lshl_b32 s79, s2, 3
	s_add_u32 s78, s78, s79
	s_lshl_b32 s78, s78, 12
	s_add_u32 s80, s28, 0x14900000
	s_addc_u32 s81, s29, 0
	s_add_u32 s80, s80, s78
	s_addc_u32 s81, s81, 0
	v_mbcnt_hi_u32_b32 v228, -1, v185
	v_lshlrev_b32_e32 v228, 3, v228
	s_nop 0
.LBB0_1195:
	ds_read_b128 v[16:19], v191
	ds_read_b128 v[20:23], v191 offset:1024
	ds_read_b128 v[24:27], v191 offset:2048
	ds_read_b128 v[28:31], v191 offset:3072
	ds_read_b128 v[0:3], v192
	ds_read_b128 v[4:7], v192 offset:1024
	ds_read_b128 v[8:11], v192 offset:2048
	ds_read_b128 v[12:15], v192 offset:3072
	s_add_u32 s52, s48, 0xfff00080
	s_addc_u32 s53, s49, -1
	s_cmp_eq_u32 s66, 60
	s_cselect_b32 s55, s39, s53
	s_cselect_b32 s54, s45, s52
	s_cselect_b32 s53, s37, s65
	s_cselect_b32 s52, s63, s64
	v_lshl_add_u64 v[218:219], s[48:49], 0, v[168:169]
	s_add_i32 m0, s26, 0xc000
	ds_read_b128 v[176:179], v193
	ds_read_b128 v[180:183], v193 offset:1024
	ds_read_b128 v[194:197], v193 offset:2048
	ds_read_b128 v[198:201], v193 offset:3072
	ds_read_b128 v[202:205], v193 offset:4096
	ds_read_b128 v[206:209], v193 offset:5120
	ds_read_b128 v[210:213], v193 offset:6144
	ds_read_b128 v[214:217], v193 offset:7168
	global_load_lds_dwordx4 v[218:219], off
	v_lshl_add_u64 v[218:219], s[48:49], 0, v[170:171]
	s_add_i32 m0, s26, 0xe000
	s_nop 0
	global_load_lds_dwordx4 v[218:219], off
	s_waitcnt vmcnt(8)
	s_add_u32 s79, s66, 2
	s_lshr_b32 s86, s79, 4
	s_lshl_b32 s86, s86, 23
	s_and_b32 s87, s79, 15
	s_lshl_b32 s87, s87, 8
	s_add_u32 s86, s86, s87
	v_add_u32_e32 v229, s86, v228
	global_load_dword v230, v229, s[80:81]
	s_nop 0
	s_waitcnt lgkmcnt(0)
	s_barrier
	s_setprio 1
	s_waitcnt lgkmcnt(0)
	v_mfma_scale_f32_16x16x128_f8f6f4 v[156:159], v[16:23], v[176:183], v[156:159], v186, v187 op_sel_hi:[0,0,0]
	v_mfma_scale_f32_16x16x128_f8f6f4 v[152:155], v[24:31], v[176:183], v[152:155], v186, v187 op_sel_hi:[0,0,0]
	v_mfma_scale_f32_16x16x128_f8f6f4 v[140:143], v[16:23], v[194:201], v[140:143], v186, v187 op_sel_hi:[0,0,0]
	v_mfma_scale_f32_16x16x128_f8f6f4 v[136:139], v[24:31], v[194:201], v[136:139], v186, v187 op_sel_hi:[0,0,0]
	v_mfma_scale_f32_16x16x128_f8f6f4 v[124:127], v[16:23], v[202:209], v[124:127], v186, v187 op_sel_hi:[0,0,0]
	v_mfma_scale_f32_16x16x128_f8f6f4 v[120:123], v[24:31], v[202:209], v[120:123], v186, v187 op_sel_hi:[0,0,0]
	v_mfma_scale_f32_16x16x128_f8f6f4 v[108:111], v[16:23], v[210:217], v[108:111], v186, v187 op_sel_hi:[0,0,0]
	v_mfma_scale_f32_16x16x128_f8f6f4 v[104:107], v[24:31], v[210:217], v[104:107], v186, v187 op_sel_hi:[0,0,0]
	s_setprio 0
	s_setprio 1
	v_mfma_scale_f32_16x16x128_f8f6f4 v[148:151], v[0:7], v[176:183], v[148:151], v186, v187 op_sel_hi:[0,0,0]
	v_mfma_scale_f32_16x16x128_f8f6f4 v[144:147], v[8:15], v[176:183], v[144:147], v186, v187 op_sel_hi:[0,0,0]
	v_mfma_scale_f32_16x16x128_f8f6f4 v[132:135], v[0:7], v[194:201], v[132:135], v186, v187 op_sel_hi:[0,0,0]
	v_mfma_scale_f32_16x16x128_f8f6f4 v[128:131], v[8:15], v[194:201], v[128:131], v186, v187 op_sel_hi:[0,0,0]
	v_mfma_scale_f32_16x16x128_f8f6f4 v[116:119], v[0:7], v[202:209], v[116:119], v186, v187 op_sel_hi:[0,0,0]
	v_mfma_scale_f32_16x16x128_f8f6f4 v[112:115], v[8:15], v[202:209], v[112:115], v186, v187 op_sel_hi:[0,0,0]
	v_mfma_scale_f32_16x16x128_f8f6f4 v[100:103], v[0:7], v[210:217], v[100:103], v186, v187 op_sel_hi:[0,0,0]
	v_mfma_scale_f32_16x16x128_f8f6f4 v[96:99], v[8:15], v[210:217], v[96:99], v186, v187 op_sel_hi:[0,0,0]
	s_setprio 0
	s_barrier
	s_add_i32 s67, s61, s17
	v_lshl_add_u64 v[176:177], s[52:53], 0, v[162:163]
	s_mov_b32 m0, s67
	ds_read_b128 v[194:197], v193 offset:16384
	ds_read_b128 v[198:201], v193 offset:17408
	ds_read_b128 v[202:205], v193 offset:18432
	ds_read_b128 v[206:209], v193 offset:19456
	ds_read_b128 v[210:213], v193 offset:20480
	ds_read_b128 v[214:217], v193 offset:21504
	ds_read_b128 v[218:221], v193 offset:22528
	ds_read_b128 v[222:225], v193 offset:23552
	global_load_lds_dwordx4 v[176:177], off
	s_add_i32 m0, s67, 0x2000
	s_add_u32 s68, s52, 0x100000
	v_lshl_add_u64 v[178:179], s[52:53], 0, v[166:167]
	s_addc_u32 s69, s53, 0
	s_add_i32 s67, s62, s17
	global_load_lds_dwordx4 v[178:179], off
	v_lshl_add_u64 v[180:181], s[68:69], 0, v[162:163]
	s_mov_b32 m0, s67
	v_lshl_add_u64 v[182:183], s[54:55], 0, v[164:165]
	global_load_lds_dwordx4 v[180:181], off
	v_lshl_add_u64 v[180:181], s[68:69], 0, v[166:167]
	s_add_i32 m0, s67, 0x2000
	s_nop 0
	global_load_lds_dwordx4 v[180:181], off
	v_lshl_add_u64 v[180:181], s[54:55], 0, v[160:161]
	s_mov_b32 m0, s26
	s_nop 0
	global_load_lds_dwordx4 v[180:181], off
	s_mov_b32 m0, s27
	s_nop 0
	global_load_lds_dwordx4 v[182:183], off
	s_waitcnt vmcnt(9)
	s_waitcnt lgkmcnt(0)
	s_barrier
	s_setprio 1
	s_waitcnt lgkmcnt(0)
	v_mfma_scale_f32_16x16x128_f8f6f4 v[92:95], v[16:23], v[194:201], v[92:95], v186, v187 op_sel_hi:[0,0,0]
	v_mfma_scale_f32_16x16x128_f8f6f4 v[88:91], v[24:31], v[194:201], v[88:91], v186, v187 op_sel_hi:[0,0,0]
	v_mfma_scale_f32_16x16x128_f8f6f4 v[76:79], v[16:23], v[202:209], v[76:79], v186, v187 op_sel_hi:[0,0,0]
	v_mfma_scale_f32_16x16x128_f8f6f4 v[72:75], v[24:31], v[202:209], v[72:75], v186, v187 op_sel_hi:[0,0,0]
	v_mfma_scale_f32_16x16x128_f8f6f4 v[60:63], v[16:23], v[210:217], v[60:63], v186, v187 op_sel_hi:[0,0,0]
	v_mfma_scale_f32_16x16x128_f8f6f4 v[56:59], v[24:31], v[210:217], v[56:59], v186, v187 op_sel_hi:[0,0,0]
	v_mfma_scale_f32_16x16x128_f8f6f4 v[44:47], v[16:23], v[218:225], v[44:47], v186, v187 op_sel_hi:[0,0,0]
	v_mfma_scale_f32_16x16x128_f8f6f4 v[40:43], v[24:31], v[218:225], v[40:43], v186, v187 op_sel_hi:[0,0,0]
	s_setprio 0
	s_setprio 1
	v_mfma_scale_f32_16x16x128_f8f6f4 v[84:87], v[0:7], v[194:201], v[84:87], v186, v187 op_sel_hi:[0,0,0]
	v_mfma_scale_f32_16x16x128_f8f6f4 v[80:83], v[8:15], v[194:201], v[80:83], v186, v187 op_sel_hi:[0,0,0]
	v_mfma_scale_f32_16x16x128_f8f6f4 v[68:71], v[0:7], v[202:209], v[68:71], v186, v187 op_sel_hi:[0,0,0]
	v_mfma_scale_f32_16x16x128_f8f6f4 v[64:67], v[8:15], v[202:209], v[64:67], v186, v187 op_sel_hi:[0,0,0]
	v_mfma_scale_f32_16x16x128_f8f6f4 v[52:55], v[0:7], v[210:217], v[52:55], v186, v187 op_sel_hi:[0,0,0]
	v_mfma_scale_f32_16x16x128_f8f6f4 v[48:51], v[8:15], v[210:217], v[48:51], v186, v187 op_sel_hi:[0,0,0]
	v_mfma_scale_f32_16x16x128_f8f6f4 v[36:39], v[0:7], v[218:225], v[36:39], v186, v187 op_sel_hi:[0,0,0]
	v_mfma_scale_f32_16x16x128_f8f6f4 v[32:35], v[8:15], v[218:225], v[32:35], v186, v187 op_sel_hi:[0,0,0]
	s_setprio 0
	s_barrier
	s_add_i32 s67, 0, 0x18000
	s_add_i32 s68, 0, 0x1c000
	v_add_u32_e32 v12, s67, v189
	v_add_u32_e32 v28, s68, v189
	ds_read_b128 v[0:3], v12
	ds_read_b128 v[4:7], v12 offset:1024
	ds_read_b128 v[8:11], v12 offset:2048
	ds_read_b128 v[12:15], v12 offset:3072
	ds_read_b128 v[16:19], v28
	ds_read_b128 v[20:23], v28 offset:1024
	ds_read_b128 v[24:27], v28 offset:2048
	ds_read_b128 v[28:31], v28 offset:3072
	s_add_u32 s54, s54, 0x100000
	s_addc_u32 s55, s55, 0
	s_mov_b32 m0, s33
	v_lshl_add_u64 v[226:227], s[54:55], 0, v[160:161]
	ds_read_b128 v[194:197], v193 offset:32768
	ds_read_b128 v[198:201], v193 offset:33792
	ds_read_b128 v[202:205], v193 offset:34816
	ds_read_b128 v[206:209], v193 offset:35840
	ds_read_b128 v[210:213], v193 offset:36864
	ds_read_b128 v[214:217], v193 offset:37888
	ds_read_b128 v[218:221], v193 offset:38912
	ds_read_b128 v[222:225], v193 offset:39936
	global_load_lds_dwordx4 v[226:227], off
	v_lshl_add_u64 v[226:227], s[54:55], 0, v[164:165]
	s_mov_b32 m0, s35
	s_nop 0
	global_load_lds_dwordx4 v[226:227], off
	s_waitcnt vmcnt(9)
	s_waitcnt lgkmcnt(0)
	s_barrier
	s_setprio 1
	s_waitcnt lgkmcnt(0)
	v_mfma_scale_f32_16x16x128_f8f6f4 v[156:159], v[0:7], v[194:201], v[156:159], v186, v187 op_sel_hi:[0,0,0]
	v_mfma_scale_f32_16x16x128_f8f6f4 v[152:155], v[8:15], v[194:201], v[152:155], v186, v187 op_sel_hi:[0,0,0]
	v_mfma_scale_f32_16x16x128_f8f6f4 v[140:143], v[0:7], v[202:209], v[140:143], v186, v187 op_sel_hi:[0,0,0]
	v_mfma_scale_f32_16x16x128_f8f6f4 v[136:139], v[8:15], v[202:209], v[136:139], v186, v187 op_sel_hi:[0,0,0]
	v_mfma_scale_f32_16x16x128_f8f6f4 v[124:127], v[0:7], v[210:217], v[124:127], v186, v187 op_sel_hi:[0,0,0]
	v_mfma_scale_f32_16x16x128_f8f6f4 v[120:123], v[8:15], v[210:217], v[120:123], v186, v187 op_sel_hi:[0,0,0]
	v_mfma_scale_f32_16x16x128_f8f6f4 v[108:111], v[0:7], v[218:225], v[108:111], v186, v187 op_sel_hi:[0,0,0]
	v_mfma_scale_f32_16x16x128_f8f6f4 v[104:107], v[8:15], v[218:225], v[104:107], v186, v187 op_sel_hi:[0,0,0]
	s_setprio 0
	s_setprio 1
	v_mfma_scale_f32_16x16x128_f8f6f4 v[148:151], v[16:23], v[194:201], v[148:151], v186, v187 op_sel_hi:[0,0,0]
	v_mfma_scale_f32_16x16x128_f8f6f4 v[144:147], v[24:31], v[194:201], v[144:147], v186, v187 op_sel_hi:[0,0,0]
	v_mfma_scale_f32_16x16x128_f8f6f4 v[132:135], v[16:23], v[202:209], v[132:135], v186, v187 op_sel_hi:[0,0,0]
	v_mfma_scale_f32_16x16x128_f8f6f4 v[128:131], v[24:31], v[202:209], v[128:131], v186, v187 op_sel_hi:[0,0,0]
	v_mfma_scale_f32_16x16x128_f8f6f4 v[116:119], v[16:23], v[210:217], v[116:119], v186, v187 op_sel_hi:[0,0,0]
	v_mfma_scale_f32_16x16x128_f8f6f4 v[112:115], v[24:31], v[210:217], v[112:115], v186, v187 op_sel_hi:[0,0,0]
	v_mfma_scale_f32_16x16x128_f8f6f4 v[100:103], v[16:23], v[218:225], v[100:103], v186, v187 op_sel_hi:[0,0,0]
	v_mfma_scale_f32_16x16x128_f8f6f4 v[96:99], v[24:31], v[218:225], v[96:99], v186, v187 op_sel_hi:[0,0,0]
	s_setprio 0
	s_barrier
	s_add_i32 s54, s67, s17
	v_lshl_add_u64 v[176:177], v[176:177], 0, s[10:11]
	s_mov_b32 m0, s54
	ds_read_b128 v[194:197], v193 offset:49152
	ds_read_b128 v[198:201], v193 offset:50176
	ds_read_b128 v[202:205], v193 offset:51200
	ds_read_b128 v[206:209], v193 offset:52224
	ds_read_b128 v[210:213], v193 offset:53248
	ds_read_b128 v[214:217], v193 offset:54272
	ds_read_b128 v[218:221], v193 offset:55296
	ds_read_b128 v[222:225], v193 offset:56320
	global_load_lds_dwordx4 v[176:177], off
	s_add_i32 m0, s54, 0x2000
	s_add_u32 s52, s52, 0x100080
	v_lshl_add_u64 v[176:177], v[178:179], 0, s[10:11]
	s_addc_u32 s53, s53, 0
	s_add_i32 s54, s68, s17
	global_load_lds_dwordx4 v[176:177], off
	v_lshl_add_u64 v[176:177], s[52:53], 0, v[162:163]
	s_mov_b32 m0, s54
	s_nop 0
	global_load_lds_dwordx4 v[176:177], off
	v_lshl_add_u64 v[176:177], s[52:53], 0, v[166:167]
	s_add_i32 m0, s54, 0x2000
	s_nop 0
	global_load_lds_dwordx4 v[176:177], off
	v_lshl_add_u64 v[176:177], v[180:181], 0, s[10:11]
	s_mov_b32 m0, s56
	s_nop 0
	global_load_lds_dwordx4 v[176:177], off
	v_lshl_add_u64 v[176:177], v[182:183], 0, s[10:11]
	s_mov_b32 m0, s57
	s_nop 0
	global_load_lds_dwordx4 v[176:177], off
	s_waitcnt vmcnt(8)
	s_waitcnt lgkmcnt(0)
	s_barrier
	s_setprio 1
	s_waitcnt lgkmcnt(0)
	v_mfma_scale_f32_16x16x128_f8f6f4 v[92:95], v[0:7], v[194:201], v[92:95], v186, v187 op_sel_hi:[0,0,0]
	v_mfma_scale_f32_16x16x128_f8f6f4 v[88:91], v[8:15], v[194:201], v[88:91], v186, v187 op_sel_hi:[0,0,0]
	v_mfma_scale_f32_16x16x128_f8f6f4 v[76:79], v[0:7], v[202:209], v[76:79], v186, v187 op_sel_hi:[0,0,0]
	v_mfma_scale_f32_16x16x128_f8f6f4 v[72:75], v[8:15], v[202:209], v[72:75], v186, v187 op_sel_hi:[0,0,0]
	v_mfma_scale_f32_16x16x128_f8f6f4 v[60:63], v[0:7], v[210:217], v[60:63], v186, v187 op_sel_hi:[0,0,0]
	v_mfma_scale_f32_16x16x128_f8f6f4 v[56:59], v[8:15], v[210:217], v[56:59], v186, v187 op_sel_hi:[0,0,0]
	v_mfma_scale_f32_16x16x128_f8f6f4 v[44:47], v[0:7], v[218:225], v[44:47], v186, v187 op_sel_hi:[0,0,0]
	v_mfma_scale_f32_16x16x128_f8f6f4 v[40:43], v[8:15], v[218:225], v[40:43], v186, v187 op_sel_hi:[0,0,0]
	s_setprio 0
	s_setprio 1
	v_mfma_scale_f32_16x16x128_f8f6f4 v[84:87], v[16:23], v[194:201], v[84:87], v186, v187 op_sel_hi:[0,0,0]
	v_mfma_scale_f32_16x16x128_f8f6f4 v[80:83], v[24:31], v[194:201], v[80:83], v186, v187 op_sel_hi:[0,0,0]
	v_mfma_scale_f32_16x16x128_f8f6f4 v[68:71], v[16:23], v[202:209], v[68:71], v186, v187 op_sel_hi:[0,0,0]
	v_mfma_scale_f32_16x16x128_f8f6f4 v[64:67], v[24:31], v[202:209], v[64:67], v186, v187 op_sel_hi:[0,0,0]
	v_mfma_scale_f32_16x16x128_f8f6f4 v[52:55], v[16:23], v[210:217], v[52:55], v186, v187 op_sel_hi:[0,0,0]
	v_mfma_scale_f32_16x16x128_f8f6f4 v[48:51], v[24:31], v[210:217], v[48:51], v186, v187 op_sel_hi:[0,0,0]
	v_mfma_scale_f32_16x16x128_f8f6f4 v[36:39], v[16:23], v[218:225], v[36:39], v186, v187 op_sel_hi:[0,0,0]
	v_mfma_scale_f32_16x16x128_f8f6f4 v[32:35], v[24:31], v[218:225], v[32:35], v186, v187 op_sel_hi:[0,0,0]
	s_setprio 0
	s_barrier
	s_add_i32 s66, s66, 2
	s_add_u32 s48, s48, 0x100
	s_addc_u32 s49, s49, 0
	s_add_u32 s64, s64, 0x100
	s_addc_u32 s65, s65, 0
	s_cmp_gt_u32 s66, 61
	s_cbranch_scc0 .LBB0_1195
	s_and_b64 vcc, exec, s[12:13]
	s_cbranch_vccz .LBB0_1198
	s_barrier
